# prologue weight transposition: kb-fastest item order (long contiguous runs on both the f32 read side and the bf16 write side)
# speedup vs baseline: 1.0157x; 1.0021x over previous
.LBB0_8:
	s_nop 0
	v_readlane_b32 s4, v255, 2
	v_readlane_b32 s6, v255, 4
	s_cmp_lt_i32 s6, 1
	v_readlane_b32 s7, v255, 5
	s_cselect_b64 s[22:23], -1, 0
	s_cmp_gt_i32 s6, 0
	v_readlane_b32 s5, v255, 3
	s_cselect_b64 s[2:3], -1, 0
	s_cmp_lt_i32 s7, 1
	s_cselect_b64 s[4:5], -1, 0
	s_or_b64 s[2:3], s[2:3], s[4:5]
	s_and_b64 vcc, exec, s[2:3]
	s_cbranch_vccnz .LBB0_219
	s_mov_b64 s[24:25], s[0:1]
	s_mov_b32 s26, s12
	s_mov_b32 s28, s13
	v_mov_b32_e32 v44, v220
	s_nop 0
	v_readfirstlane_b32 s2, v44
	s_ashr_i32 s27, s2, 6
	s_lshl_b32 s2, s26, 3
	v_and_b32_e32 v46, 63, v44
	s_add_i32 s29, s27, s2
	s_cmp_gt_i32 s29, 0xd7ff
	v_lshlrev_b32_e32 v13, 3, v46
	s_cbranch_scc1 .LBB0_58
	s_lshl_b32 s30, s28, 3
	s_load_dwordx2 s[2:3], s[24:25], 0x68
	s_load_dwordx2 s[4:5], s[24:25], 0xd0
	s_load_dwordx2 s[6:7], s[24:25], 0xc0
	s_load_dwordx2 s[8:9], s[24:25], 0xe8
	v_lshrrev_b32_e32 v0, 3, v46
	v_and_b32_e32 v1, 7, v46
	v_lshlrev_b32_e32 v2, 4, v1
	v_lshlrev_b32_e32 v3, 3, v0
	v_lshlrev_b32_e32 v4, 2, v1
	v_lshlrev_b32_e32 v5, 4, v0
	s_waitcnt lgkmcnt(0)
	s_mov_b32 s11, s29
	s_cmp_ge_u32 s11, 0x6c00
	s_cselect_b32 s16, 0x6c00, 0
	s_cselect_b32 s10, 2, 0
	s_sub_u32 s11, s11, s16
	s_cmp_ge_u32 s11, 0x3600
	s_cselect_b32 s16, 0x3600, 0
	s_cselect_b32 s17, 1, 0
	s_sub_u32 s11, s11, s16
	s_add_u32 s10, s10, s17
	s_cmp_lt_u32 s11, 0x2400
	s_cbranch_scc1 .Ltr_in1
	s_cmp_lt_u32 s11, 0x3400
	s_cbranch_scc1 .Ltr_out1
	s_sub_u32 s11, s11, 0x3400
	s_and_b32 s16, s11, 15
	s_lshr_b32 s17, s11, 4
	s_movk_i32 s14, 0x2000
	s_movk_i32 s15, 0x800
	s_mov_b32 s34, 0x10000
	s_lshl_b32 s31, s10, 23
	s_lshl_b32 s11, s16, 19
	s_add_u32 s31, s31, s11
	s_lshl_b32 s11, s17, 8
	s_add_u32 s31, s31, s11
	s_add_u32 s31, s6, s31
	s_addc_u32 s11, s7, 0
	s_bfe_u32 s14, s17, 0x30001
	s_lshl_b32 s14, s14, 8
	s_lshr_b32 s15, s17, 4
	s_lshl_b32 s15, s15, 7
	s_add_u32 s14, s14, s15
	s_and_b32 s15, s17, 1
	s_lshl_b32 s15, s15, 6
	s_add_u32 s14, s14, s15
	s_lshl_b32 s14, s14, 11
	s_lshl_b32 s15, s16, 7
	s_add_u32 s14, s14, s15
	s_lshl_b32 s15, s10, 22
	s_add_u32 s14, s14, s15
	s_add_u32 s17, s14, 0xae00000
	s_mov_b32 s16, s31
	s_mov_b32 s31, s17
	s_mov_b32 s17, s11
	s_movk_i32 s14, 0x2000
	s_movk_i32 s15, 0x800
	s_branch .Ltr_dec1
.Ltr_in1:
	s_and_b32 s16, s11, 63
	s_lshr_b32 s17, s11, 6
	s_mov_b32 s34, 0x40000
	s_mul_i32 s31, s10, 0x9000000
	s_mul_i32 s11, s16, 0x240000
	s_add_u32 s31, s31, s11
	s_lshl_b32 s11, s17, 8
	s_add_u32 s31, s31, s11
	s_add_u32 s14, s2, s31
	s_addc_u32 s15, s3, 0
	s_mul_i32 s31, s10, 0x4800000
	s_lshl_b32 s11, s17, 19
	s_add_u32 s31, s31, s11
	s_lshl_b32 s11, s16, 7
	s_add_u32 s31, s31, s11
	s_add_u32 s31, s31, 0x14600000
	s_mov_b32 s16, s14
	s_mov_b32 s17, s15
	s_mov_b32 s14, 0x9000
	s_movk_i32 s15, 0x2000
	s_branch .Ltr_dec1
.Ltr_out1:
	s_sub_u32 s11, s11, 0x2400
	s_and_b32 s16, s11, 63
	s_lshr_b32 s17, s11, 6
	s_mov_b32 s34, 0x40000
	s_lshl_b32 s31, s10, 26
	s_lshl_b32 s11, s16, 20
	s_add_u32 s31, s31, s11
	s_lshl_b32 s11, s17, 8
	s_add_u32 s31, s31, s11
	s_add_u32 s14, s4, s31
	s_addc_u32 s15, s5, 0
	s_lshl_b32 s31, s10, 25
	s_lshl_b32 s11, s17, 19
	s_add_u32 s31, s31, s11
	s_lshl_b32 s11, s16, 7
	s_add_u32 s31, s31, s11
	s_add_u32 s31, s31, 0xc600000
	s_mov_b32 s16, s14
	s_mov_b32 s17, s15
	s_movk_i32 s14, 0x4000
	s_movk_i32 s15, 0x2000

.Ltr_loop:
	s_add_u32 s29, s29, s30
	s_cmp_gt_u32 s29, 0xd7ff
	s_cbranch_scc1 .Ltr_lastA
	s_mov_b32 s11, s29
	s_cmp_ge_u32 s11, 0x6c00
	s_cselect_b32 s16, 0x6c00, 0
	s_cselect_b32 s10, 2, 0
	s_sub_u32 s11, s11, s16
	s_cmp_ge_u32 s11, 0x3600
	s_cselect_b32 s16, 0x3600, 0
	s_cselect_b32 s17, 1, 0
	s_sub_u32 s11, s11, s16
	s_add_u32 s10, s10, s17
	s_cmp_lt_u32 s11, 0x2400
	s_cbranch_scc1 .Ltr_in2
	s_cmp_lt_u32 s11, 0x3400
	s_cbranch_scc1 .Ltr_out2
	s_sub_u32 s11, s11, 0x3400
	s_and_b32 s16, s11, 15
	s_lshr_b32 s17, s11, 4
	s_movk_i32 s14, 0x2000
	s_movk_i32 s15, 0x800
	s_mov_b32 s35, 0x10000
	s_lshl_b32 s31, s10, 23
	s_lshl_b32 s11, s16, 19
	s_add_u32 s31, s31, s11
	s_lshl_b32 s11, s17, 8
	s_add_u32 s31, s31, s11
	s_add_u32 s31, s6, s31
	s_addc_u32 s11, s7, 0
	s_bfe_u32 s14, s17, 0x30001
	s_lshl_b32 s14, s14, 8
	s_lshr_b32 s15, s17, 4
	s_lshl_b32 s15, s15, 7
	s_add_u32 s14, s14, s15
	s_and_b32 s15, s17, 1
	s_lshl_b32 s15, s15, 6
	s_add_u32 s14, s14, s15
	s_lshl_b32 s14, s14, 11
	s_lshl_b32 s15, s16, 7
	s_add_u32 s14, s14, s15
	s_lshl_b32 s15, s10, 22
	s_add_u32 s14, s14, s15
	s_add_u32 s17, s14, 0xae00000
	s_mov_b32 s16, s31
	s_mov_b32 s31, s17
	s_mov_b32 s17, s11
	s_movk_i32 s14, 0x2000
	s_movk_i32 s15, 0x800
	s_branch .Ltr_dec2
.Ltr_in2:
	s_and_b32 s16, s11, 63
	s_lshr_b32 s17, s11, 6
	s_mov_b32 s35, 0x40000
	s_mul_i32 s31, s10, 0x9000000
	s_mul_i32 s11, s16, 0x240000
	s_add_u32 s31, s31, s11
	s_lshl_b32 s11, s17, 8
	s_add_u32 s31, s31, s11
	s_add_u32 s14, s2, s31
	s_addc_u32 s15, s3, 0
	s_mul_i32 s31, s10, 0x4800000
	s_lshl_b32 s11, s17, 19
	s_add_u32 s31, s31, s11
	s_lshl_b32 s11, s16, 7
	s_add_u32 s31, s31, s11
	s_add_u32 s31, s31, 0x14600000
	s_mov_b32 s16, s14
	s_mov_b32 s17, s15
	s_mov_b32 s14, 0x9000
	s_movk_i32 s15, 0x2000
	s_branch .Ltr_dec2
.Ltr_out2:
	s_sub_u32 s11, s11, 0x2400
	s_and_b32 s16, s11, 63
	s_lshr_b32 s17, s11, 6
	s_mov_b32 s35, 0x40000
	s_lshl_b32 s31, s10, 26
	s_lshl_b32 s11, s16, 20
	s_add_u32 s31, s31, s11
	s_lshl_b32 s11, s17, 8
	s_add_u32 s31, s31, s11
	s_add_u32 s14, s4, s31
	s_addc_u32 s15, s5, 0
	s_lshl_b32 s31, s10, 25
	s_lshl_b32 s11, s17, 19
	s_add_u32 s31, s31, s11
	s_lshl_b32 s11, s16, 7
	s_add_u32 s31, s31, s11
	s_add_u32 s31, s31, 0xc600000
	s_mov_b32 s16, s14
	s_mov_b32 s17, s15
	s_movk_i32 s14, 0x4000
	s_movk_i32 s15, 0x2000
.Ltr_dec2:
	s_add_u32 s40, s8, s31
	s_addc_u32 s41, s9, 0
	v_mad_u32_u24 v16, v3, s14, v2
	v_add_u32_e32 v17, s14, v16
	v_add_u32_e32 v18, s14, v17
	v_add_u32_e32 v19, s14, v18
	v_add_u32_e32 v20, s14, v19
	v_add_u32_e32 v21, s14, v20
	v_add_u32_e32 v22, s14, v21
	v_add_u32_e32 v23, s14, v22
	v_mad_u32_u24 v28, v4, s15, v5
	v_add_u32_e32 v29, s15, v28
	v_add_u32_e32 v30, s15, v29
	v_add_u32_e32 v31, s15, v30
	global_load_dwordx4 v[128:131], v16, s[16:17] nt
	global_load_dwordx4 v[132:135], v17, s[16:17] nt
	global_load_dwordx4 v[136:139], v18, s[16:17] nt
	global_load_dwordx4 v[140:143], v19, s[16:17] nt
	global_load_dwordx4 v[144:147], v20, s[16:17] nt
	global_load_dwordx4 v[148:151], v21, s[16:17] nt
	global_load_dwordx4 v[152:155], v22, s[16:17] nt
	global_load_dwordx4 v[156:159], v23, s[16:17] nt
	global_load_dwordx4 v[160:163], v16, s[16:17] offset:128 nt
	global_load_dwordx4 v[164:167], v17, s[16:17] offset:128 nt
	global_load_dwordx4 v[168:171], v18, s[16:17] offset:128 nt
	global_load_dwordx4 v[172:175], v19, s[16:17] offset:128 nt
	global_load_dwordx4 v[176:179], v20, s[16:17] offset:128 nt
	global_load_dwordx4 v[180:183], v21, s[16:17] offset:128 nt
	global_load_dwordx4 v[184:187], v22, s[16:17] offset:128 nt
	global_load_dwordx4 v[188:191], v23, s[16:17] offset:128 nt
	s_waitcnt vmcnt(16)
	v_cvt_pk_bf16_f32 v192, v64, v68
	v_cvt_pk_bf16_f32 v193, v72, v76
	v_cvt_pk_bf16_f32 v194, v80, v84
	v_cvt_pk_bf16_f32 v195, v88, v92
	v_cvt_pk_bf16_f32 v196, v65, v69
	v_cvt_pk_bf16_f32 v197, v73, v77
	v_cvt_pk_bf16_f32 v198, v81, v85
	v_cvt_pk_bf16_f32 v199, v89, v93
	v_cvt_pk_bf16_f32 v200, v66, v70
	v_cvt_pk_bf16_f32 v201, v74, v78
	v_cvt_pk_bf16_f32 v202, v82, v86
	v_cvt_pk_bf16_f32 v203, v90, v94
	v_cvt_pk_bf16_f32 v204, v67, v71
	v_cvt_pk_bf16_f32 v205, v75, v79
	v_cvt_pk_bf16_f32 v206, v83, v87
	v_cvt_pk_bf16_f32 v207, v91, v95
	global_store_dwordx4 v24, v[192:195], s[18:19] nt
	global_store_dwordx4 v25, v[196:199], s[18:19] nt
	global_store_dwordx4 v26, v[200:203], s[18:19] nt
	global_store_dwordx4 v27, v[204:207], s[18:19] nt
	v_cvt_pk_bf16_f32 v48, v96, v100
	v_cvt_pk_bf16_f32 v49, v104, v108
	v_cvt_pk_bf16_f32 v50, v112, v116
	v_cvt_pk_bf16_f32 v51, v120, v124
	v_cvt_pk_bf16_f32 v52, v97, v101
	v_cvt_pk_bf16_f32 v53, v105, v109
	v_cvt_pk_bf16_f32 v54, v113, v117
	v_cvt_pk_bf16_f32 v55, v121, v125
	v_cvt_pk_bf16_f32 v56, v98, v102
	v_cvt_pk_bf16_f32 v57, v106, v110
	v_cvt_pk_bf16_f32 v58, v114, v118
	v_cvt_pk_bf16_f32 v59, v122, v126
	v_cvt_pk_bf16_f32 v60, v99, v103
	v_cvt_pk_bf16_f32 v61, v107, v111
	v_cvt_pk_bf16_f32 v62, v115, v119
	v_cvt_pk_bf16_f32 v63, v123, v127
	s_add_u32 s10, s18, s34
	s_addc_u32 s11, s19, 0
	global_store_dwordx4 v24, v[48:51], s[10:11] nt
	global_store_dwordx4 v25, v[52:55], s[10:11] nt
	global_store_dwordx4 v26, v[56:59], s[10:11] nt
	global_store_dwordx4 v27, v[60:63], s[10:11] nt
	s_add_u32 s29, s29, s30
	s_cmp_gt_u32 s29, 0xd7ff
	s_cbranch_scc1 .Ltr_lastB
	s_mov_b32 s11, s29
	s_cmp_ge_u32 s11, 0x6c00
	s_cselect_b32 s16, 0x6c00, 0
	s_cselect_b32 s10, 2, 0
	s_sub_u32 s11, s11, s16
	s_cmp_ge_u32 s11, 0x3600
	s_cselect_b32 s16, 0x3600, 0
	s_cselect_b32 s17, 1, 0
	s_sub_u32 s11, s11, s16
	s_add_u32 s10, s10, s17
	s_cmp_lt_u32 s11, 0x2400
	s_cbranch_scc1 .Ltr_in3
	s_cmp_lt_u32 s11, 0x3400
	s_cbranch_scc1 .Ltr_out3
	s_sub_u32 s11, s11, 0x3400
	s_and_b32 s16, s11, 15
	s_lshr_b32 s17, s11, 4
	s_movk_i32 s14, 0x2000
	s_movk_i32 s15, 0x800
	s_mov_b32 s34, 0x10000
	s_lshl_b32 s31, s10, 23
	s_lshl_b32 s11, s16, 19
	s_add_u32 s31, s31, s11
	s_lshl_b32 s11, s17, 8
	s_add_u32 s31, s31, s11
	s_add_u32 s31, s6, s31
	s_addc_u32 s11, s7, 0
	s_bfe_u32 s14, s17, 0x30001
	s_lshl_b32 s14, s14, 8
	s_lshr_b32 s15, s17, 4
	s_lshl_b32 s15, s15, 7
	s_add_u32 s14, s14, s15
	s_and_b32 s15, s17, 1
	s_lshl_b32 s15, s15, 6
	s_add_u32 s14, s14, s15
	s_lshl_b32 s14, s14, 11
	s_lshl_b32 s15, s16, 7
	s_add_u32 s14, s14, s15
	s_lshl_b32 s15, s10, 22
	s_add_u32 s14, s14, s15
	s_add_u32 s17, s14, 0xae00000
	s_mov_b32 s16, s31
	s_mov_b32 s31, s17
	s_mov_b32 s17, s11
	s_movk_i32 s14, 0x2000
	s_movk_i32 s15, 0x800
	s_branch .Ltr_dec3
